# backward HGRN output pass spread over all 256 workgroups (4 items on waves 0-3 each) instead of 8 items on half the grid
# speedup vs baseline: 1.0152x; 1.0092x over previous
; __device__ __forceinline__ void hgrn_state_load(const float* sb, f32x4 (&Sacc)[4][4], int fr, int quad) {
; #pragma unroll
;     for (int kt = 0; kt < 4; ++kt)
; #pragma unroll
;         for (int vt = 0; vt < 4; ++vt)
; #pragma unroll
;             for (int r = 0; r < 4; ++r) Sacc[kt][vt][r] = sb[(16 * kt + 4 * quad + r) * 64 + 16 * vt + fr];
; }
; __global__ void __launch_bounds__(NTHR, 2) fwd_megakernel(Params prm) {
;     ...
;         for (int _m = 0; _m < REP_MIXB; ++_m) for (int it = bid * 8 + C.wave; it < 1024; it += G * 8) hgrn_pass3_item<1>(C, l, it);
.Lmy_w4_end:
	s_or_b64 exec, exec, s[4:5]
	v_mov_b32_e32 v0, v224
	s_barrier
	v_readlane_b32 s5, v253, 32
	v_readfirstlane_b32 s0, v0
	s_ashr_i32 s4, s0, 6
	s_add_i32 s48, s4, s5
	s_cmpk_lg_i32 s26, 0x100
	s_cbranch_scc1 .Lmy_h3_generic
	s_lshr_b32 s48, s5, 1
	s_add_i32 s48, s48, s4
	s_cmp_gt_u32 s4, 3
	s_cselect_b32 s48, 0x400, s48
.Lmy_h3_generic:
	s_mov_b64 s[0:1], 0
	s_cmpk_gt_i32 s48, 0x3ff
	v_readlane_b32 s40, v255, 7
	s_cbranch_scc1 .LBB0_648
	v_bfe_u32 v3, v0, 4, 2
	v_and_b32_e32 v1, 15, v0
	v_lshlrev_b32_e32 v5, 8, v3
	v_or_b32_e32 v7, 16, v1
	v_or_b32_e32 v9, 32, v1
	v_or_b32_e32 v11, 48, v1
	v_or_b32_e32 v15, 0x440, v5
	v_or_b32_e32 v6, v15, v1
	v_or_b32_e32 v17, 0x480, v5
	v_or_b32_e32 v14, v15, v7
	v_or_b32_e32 v22, v15, v9
	v_or_b32_e32 v30, v15, v11
	v_or_b32_e32 v15, 0x840, v5
	s_add_u32 s0, s24, s0
	s_mulk_i32 s4, 0x3800
	v_or_b32_e32 v13, 0x400, v5
	v_or_b32_e32 v8, v17, v1
	v_or_b32_e32 v16, v17, v7
	v_or_b32_e32 v24, v17, v9
	v_or_b32_e32 v32, v17, v11
	v_or_b32_e32 v38, v15, v1
	v_or_b32_e32 v17, 0x880, v5
	v_or_b32_e32 v46, v15, v7
	v_or_b32_e32 v54, v15, v9
	v_or_b32_e32 v62, v15, v11
	v_or_b32_e32 v15, 0xc40, v5
	s_addc_u32 s1, s25, s1
	s_add_i32 s49, s4, 0
	v_or_b32_e32 v4, v13, v1
	v_or_b32_e32 v12, v13, v7
	v_or_b32_e32 v20, v13, v9
	v_or_b32_e32 v28, v13, v11
	v_or_b32_e32 v13, 0x800, v5
	v_or_b32_e32 v40, v17, v1
	v_or_b32_e32 v48, v17, v7
	v_or_b32_e32 v56, v17, v9
	v_or_b32_e32 v66, v17, v11
	v_or_b32_e32 v72, v15, v1
	v_or_b32_e32 v17, 0xc80, v5
	v_or_b32_e32 v80, v15, v7
	v_or_b32_e32 v88, v15, v9
	v_or_b32_e32 v96, v15, v11
	v_lshlrev_b32_e32 v120, 2, v3
	v_lshlrev_b32_e32 v121, 3, v3
	v_bfe_u32 v15, v0, 2, 2
	s_add_u32 s53, s0, 0x1a180000
	v_or_b32_e32 v19, 0x4c0, v5
	v_or_b32_e32 v36, v13, v1
	v_or_b32_e32 v44, v13, v7
	v_or_b32_e32 v52, v13, v9
	v_or_b32_e32 v60, v13, v11
	v_or_b32_e32 v13, 0xc00, v5
	v_or_b32_e32 v74, v17, v1
	v_or_b32_e32 v82, v17, v7
	v_or_b32_e32 v90, v17, v9
	v_or_b32_e32 v98, v17, v11
	v_mul_u32_u24_e32 v3, 0x48, v1
	v_or_b32_e32 v17, v120, v15
	v_or_b32_e32 v15, v121, v15
	v_and_b32_e32 v118, 63, v0
	s_addc_u32 s68, s1, 0
	v_or_b32_e32 v10, v19, v1
	v_or_b32_e32 v18, v19, v7
	v_or_b32_e32 v26, v19, v9
	v_or_b32_e32 v34, v19, v11
	v_or_b32_e32 v19, 0x8c0, v5
	v_or_b32_e32 v70, v13, v1
	v_or_b32_e32 v78, v13, v7
	v_or_b32_e32 v86, v13, v9
	v_or_b32_e32 v94, v13, v11
	v_lshlrev_b32_e32 v3, 1, v3
	v_and_b32_e32 v13, 48, v0
	v_lshlrev_b32_e32 v0, 3, v0
	v_mul_u32_u24_e32 v15, 0x48, v15
	v_or_b32_e32 v42, v19, v1
	v_or_b32_e32 v50, v19, v7
	v_or_b32_e32 v58, v19, v9
	v_or_b32_e32 v68, v19, v11
	v_or_b32_e32 v19, 0xcc0, v5
	s_add_u32 s69, s0, 0x7000000
	v_add3_u32 v123, s49, v3, v13
	v_sub_u32_e32 v13, v1, v120
	v_mul_u32_u24_e32 v17, 0x90, v17
	v_and_b32_e32 v0, 24, v0
	v_lshlrev_b32_e32 v15, 1, v15
	v_lshlrev_b32_e32 v64, 1, v1
	v_or_b32_e32 v2, v5, v1
	v_or_b32_e32 v76, v19, v1
	s_addc_u32 s70, s1, 0
	v_add3_u32 v124, s49, v17, v0
	v_add3_u32 v125, s49, v15, v0
	v_lshl_add_u64 v[0:1], s[0:1], 0, v[64:65]
	s_mov_b64 s[0:1], 0x4000000
	v_cmp_gt_i32_e64 s[4:5], 2, v13
	v_cmp_gt_i32_e64 s[42:43], 3, v13
	v_lshl_add_u64 v[114:115], v[0:1], 0, s[0:1]
	v_cmp_gt_i32_e64 s[0:1], 1, v13
	s_and_b64 s[20:21], s[42:43], s[4:5]
	v_or_b32_e32 v84, v19, v7
	v_or_b32_e32 v92, v19, v9
	v_or_b32_e32 v100, v19, v11
	v_add_u32_e32 v122, s49, v121
	v_cmp_gt_i32_e32 vcc, 0, v13
	v_or_b32_e32 v0, v5, v7
	v_or_b32_e32 v64, v5, v9
	v_or_b32_e32 v102, v5, v11
	s_and_b64 s[38:39], s[20:21], s[0:1]
	v_lshl_add_u32 v119, v118, 2, s49
	v_add_u32_e32 v126, v122, v3
	v_lshlrev_b32_e32 v127, 2, v2
	v_lshlrev_b32_e32 v128, 2, v0
	v_lshlrev_b32_e32 v129, 2, v64
	v_lshlrev_b32_e32 v130, 2, v102
	v_lshlrev_b32_e32 v131, 2, v4
	v_lshlrev_b32_e32 v132, 2, v6
	v_lshlrev_b32_e32 v133, 2, v8
	v_lshlrev_b32_e32 v134, 2, v10
	v_lshlrev_b32_e32 v135, 2, v12
	v_lshlrev_b32_e32 v136, 2, v14
	v_lshlrev_b32_e32 v137, 2, v16
	v_lshlrev_b32_e32 v138, 2, v18
	v_lshlrev_b32_e32 v139, 2, v20
	v_lshlrev_b32_e32 v140, 2, v22
	v_lshlrev_b32_e32 v141, 2, v24
	v_lshlrev_b32_e32 v142, 2, v26
	v_lshlrev_b32_e32 v143, 2, v28
	v_lshlrev_b32_e32 v144, 2, v30
	v_lshlrev_b32_e32 v145, 2, v32
	v_lshlrev_b32_e32 v146, 2, v34
	v_lshlrev_b32_e32 v147, 2, v36
	v_lshlrev_b32_e32 v148, 2, v38
	v_lshlrev_b32_e32 v149, 2, v40
	v_lshlrev_b32_e32 v150, 2, v42
	v_lshlrev_b32_e32 v151, 2, v44
	v_lshlrev_b32_e32 v152, 2, v46
	v_lshlrev_b32_e32 v153, 2, v48
	v_lshlrev_b32_e32 v154, 2, v50
	v_lshlrev_b32_e32 v155, 2, v52
	v_lshlrev_b32_e32 v156, 2, v54
	v_lshlrev_b32_e32 v157, 2, v56
	v_lshlrev_b32_e32 v158, 2, v58
	v_lshlrev_b32_e32 v159, 2, v60
	v_lshlrev_b32_e32 v160, 2, v62
	v_lshlrev_b32_e32 v161, 2, v66
	v_lshlrev_b32_e32 v162, 2, v68
	v_lshlrev_b32_e32 v163, 2, v70
	v_lshlrev_b32_e32 v164, 2, v72
	v_lshlrev_b32_e32 v165, 2, v74
	v_lshlrev_b32_e32 v166, 2, v76
	v_lshlrev_b32_e32 v167, 2, v78
	v_lshlrev_b32_e32 v168, 2, v80
	v_lshlrev_b32_e32 v169, 2, v82
	v_lshlrev_b32_e32 v170, 2, v84
	v_lshlrev_b32_e32 v171, 2, v86
	v_lshlrev_b32_e32 v172, 2, v88
	v_lshlrev_b32_e32 v173, 2, v90
	v_lshlrev_b32_e32 v174, 2, v92
	v_lshlrev_b32_e32 v175, 2, v94
	v_lshlrev_b32_e32 v176, 2, v96
	v_lshlrev_b32_e32 v177, 2, v98
	v_lshlrev_b32_e32 v183, 2, v100
	s_and_b64 s[44:45], s[38:39], vcc
